# SSD states: the 32 dwordx2 state stores per wave widened to 16 dwordx4 stores via v_permlane32_swap pairing of the lane halves (store-tail widening, 7.3); on top of v52
# speedup vs baseline: 1.0076x; 1.0076x over previous
; #define LAS __attribute__((address_space(3)))
; #define SSD_SBAR() __builtin_amdgcn_sched_barrier(0)
; __device__ __forceinline__ void states_unit(Frame& F, const Ptrs& P, int b, int c, int g, int hh) {
;     ...
; #pragma unroll 2
;     for (int ks = 0; ks < 8; ++ks) {
;         s16x4 xl, xh, bl[4], bh[4];
;         f32x4 wfa = *(const LAS f32x4*)(Wf + 16 * ks + 4 * hi), wfb = *(const LAS f32x4*)(Wf + 16 * ks + 8 + 4 * hi);
;         f32x4 wba = *(const LAS f32x4*)(Wb + 16 * ks + 4 * hi), wbb = *(const LAS f32x4*)(Wb + 16 * ks + 8 + 4 * hi);
;         asm volatile("" : "+v"(wfa), "+v"(wfb), "+v"(wba), "+v"(wbb));
;         SSD_SBAR();
;         tr2(xl, xh, lbase + L_XS + hl * 16384 + (ph * 8 + ks) * 1024);
; #pragma unroll
;         for (int nb = 0; nb < 4; ++nb) tr2(bl[nb], bh[nb], lbase + L_BIMG + (nb * 8 + ks) * 1024);
;         asm volatile("s_waitcnt lgkmcnt(0)" ::: "memory"); SSD_SBAR();
;         const bf16x8 xf = scale_frag(xl, xh, wfa, wfb), xb = scale_frag(xl, xh, wba, wbb);
; #pragma unroll
;         for (int nb = 0; nb < 4; ++nb) { const bf16x8 bfr = SSD_FRAG(bl[nb], bh[nb]);
;             af[nb] = __builtin_amdgcn_mfma_f32_32x32x16_bf16(bfr, xf, af[nb], 0, 0, 0); ab[nb] = __builtin_amdgcn_mfma_f32_32x32x16_bf16(bfr, xb, ab[nb], 0, 0, 0); }
;     }
.LBB0_578:
	v_add_u32_e32 v145, s64, v142
	v_add_u32_e32 v184, s75, v142
	v_add_u32_e32 v158, 0x20600, v145
	v_add_u32_e32 v154, 0x20620, v145
	v_add_u32_e32 v150, 0x20600, v184
	v_add_u32_e32 v146, 0x20620, v184
	ds_read_b128 v[146:149], v146
	ds_read_b128 v[150:153], v150
	ds_read_b128 v[154:157], v154
	ds_read_b128 v[158:161], v158
	s_waitcnt lgkmcnt(0)
	v_add_u32_e32 v185, s2, v144
	v_add_u32_e32 v162, 0x10000, v185
	ds_read_b64_tr_b16 v[178:179],v162
	ds_read_b64_tr_b16 v[180:181],v162 offset:512
	v_add_u32_e32 v186, s2, v143
	ds_read_b64_tr_b16 v[162:163],v186
	ds_read_b64_tr_b16 v[164:165],v186 offset:512
	v_add_u32_e32 v170, 0x2000, v186
	ds_read_b64_tr_b16 v[166:167],v170
	ds_read_b64_tr_b16 v[168:169],v170 offset:512
	v_add_u32_e32 v174, 0x4000, v186
	ds_read_b64_tr_b16 v[170:171],v174
	ds_read_b64_tr_b16 v[172:173],v174 offset:512
	v_add_u32_e32 v182, 0x6000, v186
	ds_read_b64_tr_b16 v[174:175],v182
	ds_read_b64_tr_b16 v[176:177],v182 offset:512
	s_waitcnt lgkmcnt(0)
	v_and_b32_e32 v183, 0xffff0000, v178
	v_lshlrev_b32_e32 v182, 16, v178
	v_pk_mul_f32 v[158:159], v[158:159], v[182:183]
	v_pk_mul_f32 v[150:151], v[150:151], v[182:183]
	v_and_b32_e32 v183, 0xffff0000, v179
	v_lshlrev_b32_e32 v182, 16, v179
	v_and_b32_e32 v179, 0xffff0000, v180
	v_lshlrev_b32_e32 v178, 16, v180
	v_pk_mul_f32 v[160:161], v[160:161], v[182:183]
	v_pk_mul_f32 v[154:155], v[154:155], v[178:179]
	v_cvt_pk_bf16_f32 v158, v158, v159
	v_cvt_pk_bf16_f32 v159, v160, v161
	v_cvt_pk_bf16_f32 v160, v154, v155
	v_and_b32_e32 v155, 0xffff0000, v181
	v_lshlrev_b32_e32 v154, 16, v181
	v_pk_mul_f32 v[152:153], v[152:153], v[182:183]
	v_pk_mul_f32 v[146:147], v[146:147], v[178:179]
	v_pk_mul_f32 v[156:157], v[156:157], v[154:155]
	v_cvt_pk_bf16_f32 v150, v150, v151
	v_cvt_pk_bf16_f32 v151, v152, v153
	v_cvt_pk_bf16_f32 v152, v146, v147
	v_pk_mul_f32 v[146:147], v[148:149], v[154:155]
	v_cvt_pk_bf16_f32 v161, v156, v157
	v_cvt_pk_bf16_f32 v153, v146, v147
	v_add_u32_e32 v154, 0x20640, v184
	v_mfma_f32_32x32x16_bf16 v[112:127], v[162:165], v[158:161], v[112:127]
	v_add_u32_e32 v146, 0x20660, v184
	v_mfma_f32_32x32x16_bf16 v[48:63], v[162:165], v[150:153], v[48:63]
	v_add_u32_e32 v162, 0x20640, v145
	v_add_u32_e32 v145, 0x20660, v145
	v_mfma_f32_32x32x16_bf16 v[96:111], v[166:169], v[158:161], v[96:111]
	v_mfma_f32_32x32x16_bf16 v[32:47], v[166:169], v[150:153], v[32:47]
	v_mfma_f32_32x32x16_bf16 v[80:95], v[170:173], v[158:161], v[80:95]
	v_mfma_f32_32x32x16_bf16 v[16:31], v[170:173], v[150:153], v[16:31]
	v_mfma_f32_32x32x16_bf16 v[64:79], v[174:177], v[158:161], v[64:79]
	ds_read_b128 v[146:149], v146
	ds_read_b128 v[154:157], v154
	ds_read_b128 v[158:161], v145
	ds_read_b128 v[162:165], v162
	s_waitcnt lgkmcnt(0)
	v_mfma_f32_32x32x16_bf16 v[0:15], v[174:177], v[150:153], v[0:15]
	v_add_u32_e32 v145, 0x10400, v185
	ds_read_b64_tr_b16 v[178:179],v145
	ds_read_b64_tr_b16 v[180:181],v145 offset:512
	v_add_u32_e32 v145, 0x400, v186
	ds_read_b64_tr_b16 v[150:151],v145
	ds_read_b64_tr_b16 v[152:153],v145 offset:512
	v_add_u32_e32 v145, 0x2400, v186
	ds_read_b64_tr_b16 v[166:167],v145
	ds_read_b64_tr_b16 v[168:169],v145 offset:512
	v_add_u32_e32 v145, 0x4400, v186
	ds_read_b64_tr_b16 v[170:171],v145
	ds_read_b64_tr_b16 v[172:173],v145 offset:512
	v_add_u32_e32 v145, 0x6400, v186
	ds_read_b64_tr_b16 v[174:175],v145
	ds_read_b64_tr_b16 v[176:177],v145 offset:512
	s_waitcnt lgkmcnt(0)
	v_and_b32_e32 v183, 0xffff0000, v178
	v_lshlrev_b32_e32 v182, 16, v178
	v_pk_mul_f32 v[162:163], v[162:163], v[182:183]
	v_pk_mul_f32 v[154:155], v[154:155], v[182:183]
	v_and_b32_e32 v183, 0xffff0000, v179
	v_lshlrev_b32_e32 v182, 16, v179
	v_and_b32_e32 v179, 0xffff0000, v180
	v_lshlrev_b32_e32 v178, 16, v180
	v_pk_mul_f32 v[164:165], v[164:165], v[182:183]
	v_pk_mul_f32 v[158:159], v[158:159], v[178:179]
	v_cvt_pk_bf16_f32 v162, v162, v163
	v_cvt_pk_bf16_f32 v163, v164, v165
	v_cvt_pk_bf16_f32 v164, v158, v159
	v_and_b32_e32 v159, 0xffff0000, v181
	v_lshlrev_b32_e32 v158, 16, v181
	v_pk_mul_f32 v[156:157], v[156:157], v[182:183]
	v_pk_mul_f32 v[146:147], v[146:147], v[178:179]
	v_pk_mul_f32 v[160:161], v[160:161], v[158:159]
	v_cvt_pk_bf16_f32 v154, v154, v155
	v_cvt_pk_bf16_f32 v155, v156, v157
	v_cvt_pk_bf16_f32 v156, v146, v147
	v_pk_mul_f32 v[146:147], v[148:149], v[158:159]
	v_cvt_pk_bf16_f32 v165, v160, v161
	v_cvt_pk_bf16_f32 v157, v146, v147
	s_addk_i32 s2, 0x800
	v_mfma_f32_32x32x16_bf16 v[112:127], v[150:153], v[162:165], v[112:127]
	v_add_u32_e32 v142, 0x80, v142
	s_cmpk_lg_i32 s2, 0x2000
	v_mfma_f32_32x32x16_bf16 v[48:63], v[150:153], v[154:157], v[48:63]
	v_mfma_f32_32x32x16_bf16 v[96:111], v[166:169], v[162:165], v[96:111]
	v_mfma_f32_32x32x16_bf16 v[32:47], v[166:169], v[154:157], v[32:47]
	v_mfma_f32_32x32x16_bf16 v[80:95], v[170:173], v[162:165], v[80:95]
	v_mfma_f32_32x32x16_bf16 v[16:31], v[170:173], v[154:157], v[16:31]
	v_mfma_f32_32x32x16_bf16 v[64:79], v[174:177], v[162:165], v[64:79]
	v_mfma_f32_32x32x16_bf16 v[0:15], v[174:177], v[154:157], v[0:15]
	s_cbranch_scc1 .LBB0_578
; __device__ __forceinline__ unsigned cvtpk(float lo, float hi) { f32x2_t v = {lo, hi}; bf16x2_t b = __builtin_convertvector(v, bf16x2_t); return __builtin_bit_cast(unsigned, b); }
; __device__ __forceinline__ unsigned cvtpk(float lo, float hi) { f32x2_t v = {lo, hi}; bf16x2_t b = __builtin_convertvector(v, bf16x2_t); return __builtin_bit_cast(unsigned, b); }
; __device__ __forceinline__ void states_unit(Frame& F, const Ptrs& P, int b, int c, int g, int hh) {
;     ...
;     const int h = h0 + hl;
; #pragma unroll
;     for (int dir = 0; dir < 2; ++dir) {
;         unsigned char* blk = SB + ((((size_t)b * 64 + c) * 2 + dir) * 16 + h) * 16384;
; #pragma unroll
;         for (int nb = 0; nb < 4; ++nb)
; #pragma unroll
;             for (int g4 = 0; g4 < 4; ++g4) { const f32x16& a = dir ? ab[nb] : af[nb];
;                 u32x2 w; w.x = cvtpk(a[4 * g4], a[4 * g4 + 1]); w.y = cvtpk(a[4 * g4 + 2], a[4 * g4 + 3]);
;                 *(u32x2*)(blk + ((((ph * 8 + 2 * nb + (g4 >> 1)) * 2 + (g4 & 1)) * 32 + r32) * 16) + hi * 8) = w; }
;     }
	s_lshl_b32 s0, s84, 19
	s_lshl_b64 s[2:3], s[16:17], 14
	s_add_u32 s2, s58, s2
	s_addc_u32 s3, s59, s3
	v_lshlrev_b32_e32 v128, 9, v128
	v_lshl_add_u64 v[142:143], s[2:3], 0, v[128:129]
	s_lshl_b64 s[2:3], s[70:71], 25
	v_and_b32_e32 v141, 0x1f0, v141
	s_mov_b32 s1, s17
	v_lshl_add_u64 v[142:143], v[142:143], 0, s[2:3]
	v_lshl_add_u64 v[142:143], v[142:143], 0, s[0:1]
	v_or_b32_e32 v128, s74, v141
	v_cvt_pk_bf16_f32 v112, v112, v113
	v_cvt_pk_bf16_f32 v113, v114, v115
	v_cvt_pk_bf16_f32 v114, v116, v117
	v_cvt_pk_bf16_f32 v115, v118, v119
	v_cvt_pk_bf16_f32 v116, v120, v121
	v_cvt_pk_bf16_f32 v117, v122, v123
	v_cvt_pk_bf16_f32 v118, v124, v125
	v_cvt_pk_bf16_f32 v119, v126, v127
	v_lshl_add_u64 v[120:121], v[142:143], 0, v[128:129]
	v_or_b32_e32 v122, 0x1000, v128
	v_mov_b32_e32 v123, v129
	v_lshl_add_u64 v[122:123], v[142:143], 0, v[122:123]
	v_lshl_add_u64 v[124:125], v[120:121], 0, s[14:15]
	v_lshl_add_u64 v[126:127], v[122:123], 0, s[14:15]
	v_cvt_pk_bf16_f32 v96, v96, v97
	v_cvt_pk_bf16_f32 v97, v98, v99
	v_cvt_pk_bf16_f32 v98, v100, v101
	v_cvt_pk_bf16_f32 v99, v102, v103
	v_cvt_pk_bf16_f32 v100, v104, v105
	v_cvt_pk_bf16_f32 v101, v106, v107
	v_cvt_pk_bf16_f32 v102, v108, v109
	v_cvt_pk_bf16_f32 v103, v110, v111
	v_permlane32_swap_b32_e32 v112, v114
	v_permlane32_swap_b32_e32 v113, v115
	v_permlane32_swap_b32_e32 v116, v118
	v_permlane32_swap_b32_e32 v117, v119
	global_store_dwordx4 v[120:121], v[112:115], off
	global_store_dwordx4 v[120:121], v[116:119], off offset:1024
	v_cvt_pk_bf16_f32 v80, v80, v81
	v_cvt_pk_bf16_f32 v81, v82, v83
	v_cvt_pk_bf16_f32 v82, v84, v85
	v_cvt_pk_bf16_f32 v83, v86, v87
	v_cvt_pk_bf16_f32 v84, v88, v89
	v_cvt_pk_bf16_f32 v85, v90, v91
	v_cvt_pk_bf16_f32 v86, v92, v93
	v_cvt_pk_bf16_f32 v87, v94, v95
	v_permlane32_swap_b32_e32 v96, v98
	v_permlane32_swap_b32_e32 v97, v99
	v_permlane32_swap_b32_e32 v100, v102
	v_permlane32_swap_b32_e32 v101, v103
	global_store_dwordx4 v[120:121], v[96:99], off offset:2048
	global_store_dwordx4 v[120:121], v[100:103], off offset:3072
	v_cvt_pk_bf16_f32 v64, v64, v65
	v_cvt_pk_bf16_f32 v65, v66, v67
	v_cvt_pk_bf16_f32 v66, v68, v69
	v_cvt_pk_bf16_f32 v67, v70, v71
	v_cvt_pk_bf16_f32 v68, v72, v73
	v_cvt_pk_bf16_f32 v69, v74, v75
	v_cvt_pk_bf16_f32 v70, v76, v77
	v_cvt_pk_bf16_f32 v71, v78, v79
	v_permlane32_swap_b32_e32 v80, v82
	v_permlane32_swap_b32_e32 v81, v83
	v_permlane32_swap_b32_e32 v84, v86
	v_permlane32_swap_b32_e32 v85, v87
	global_store_dwordx4 v[122:123], v[80:83], off
	global_store_dwordx4 v[122:123], v[84:87], off offset:1024
	v_cvt_pk_bf16_f32 v48, v48, v49
	v_cvt_pk_bf16_f32 v49, v50, v51
	v_cvt_pk_bf16_f32 v50, v52, v53
	v_cvt_pk_bf16_f32 v51, v54, v55
	v_cvt_pk_bf16_f32 v52, v56, v57
	v_cvt_pk_bf16_f32 v53, v58, v59
	v_cvt_pk_bf16_f32 v54, v60, v61
	v_cvt_pk_bf16_f32 v55, v62, v63
	v_permlane32_swap_b32_e32 v64, v66
	v_permlane32_swap_b32_e32 v65, v67
	v_permlane32_swap_b32_e32 v68, v70
	v_permlane32_swap_b32_e32 v69, v71
	global_store_dwordx4 v[122:123], v[64:67], off offset:2048
	global_store_dwordx4 v[122:123], v[68:71], off offset:3072
	v_cvt_pk_bf16_f32 v32, v32, v33
	v_cvt_pk_bf16_f32 v33, v34, v35
	v_cvt_pk_bf16_f32 v34, v36, v37
	v_cvt_pk_bf16_f32 v35, v38, v39
	v_cvt_pk_bf16_f32 v36, v40, v41
	v_cvt_pk_bf16_f32 v37, v42, v43
	v_cvt_pk_bf16_f32 v38, v44, v45
	v_cvt_pk_bf16_f32 v39, v46, v47
	v_permlane32_swap_b32_e32 v48, v50
	v_permlane32_swap_b32_e32 v49, v51
	v_permlane32_swap_b32_e32 v52, v54
	v_permlane32_swap_b32_e32 v53, v55
	global_store_dwordx4 v[124:125], v[48:51], off
	global_store_dwordx4 v[124:125], v[52:55], off offset:1024
	v_cvt_pk_bf16_f32 v16, v16, v17
	v_cvt_pk_bf16_f32 v17, v18, v19
	v_cvt_pk_bf16_f32 v18, v20, v21
	v_cvt_pk_bf16_f32 v19, v22, v23
	v_cvt_pk_bf16_f32 v20, v24, v25
	v_cvt_pk_bf16_f32 v21, v26, v27
	v_cvt_pk_bf16_f32 v22, v28, v29
	v_cvt_pk_bf16_f32 v23, v30, v31
	v_permlane32_swap_b32_e32 v32, v34
	v_permlane32_swap_b32_e32 v33, v35
	v_permlane32_swap_b32_e32 v36, v38
	v_permlane32_swap_b32_e32 v37, v39
	global_store_dwordx4 v[124:125], v[32:35], off offset:2048
	global_store_dwordx4 v[124:125], v[36:39], off offset:3072
	v_cvt_pk_bf16_f32 v0, v0, v1
	v_cvt_pk_bf16_f32 v1, v2, v3
	v_cvt_pk_bf16_f32 v2, v4, v5
	v_cvt_pk_bf16_f32 v3, v6, v7
	v_cvt_pk_bf16_f32 v4, v8, v9
	v_cvt_pk_bf16_f32 v5, v10, v11
	v_cvt_pk_bf16_f32 v6, v12, v13
	v_cvt_pk_bf16_f32 v7, v14, v15
	v_permlane32_swap_b32_e32 v16, v18
	v_permlane32_swap_b32_e32 v17, v19
	v_permlane32_swap_b32_e32 v20, v22
	v_permlane32_swap_b32_e32 v21, v23
	global_store_dwordx4 v[126:127], v[16:19], off
	global_store_dwordx4 v[126:127], v[20:23], off offset:1024
	s_nop 1
	v_permlane32_swap_b32_e32 v0, v2
	v_permlane32_swap_b32_e32 v1, v3
	v_permlane32_swap_b32_e32 v4, v6
	v_permlane32_swap_b32_e32 v5, v7
	global_store_dwordx4 v[126:127], v[0:3], off offset:2048
	global_store_dwordx4 v[126:127], v[4:7], off offset:3072
	s_add_i32 s0, s83, 0x100
	s_cmpk_lt_i32 s83, 0x100
	s_mov_b32 s83, s0
	s_barrier
